# attention K/V LDS tile double buffered, one workgroup barrier per key tile
# speedup vs baseline: 1.0018x; 1.0018x over previous
.LBB0_337:
	s_andn2_b64 vcc, exec, s[44:45]
	s_cbranch_vccnz .LBB0_447
	s_mov_b32 s101, 0
	v_readlane_b32 s38, v254, 28
	v_readlane_b32 s46, v253, 2
	v_readlane_b32 s39, v254, 29
	v_readlane_b32 s47, v253, 3
	v_mov_b32_e32 v0, v133
	s_andn2_b64 vcc, exec, s[38:39]
	s_cbranch_vccnz .LBB0_384
	v_ashrrev_i32_e32 v4, 3, v0
	v_ashrrev_i32_e32 v5, 31, v4
	s_load_dwordx2 s[44:45], s[46:47], 0xf8
	s_nop 0
	s_load_dwordx2 s[46:47], s[46:47], 0xc0
	v_lshlrev_b64 v[6:7], 8, v[4:5]
	v_lshlrev_b32_e32 v5, 3, v0
	v_and_b32_e32 v8, 56, v5
	v_add_u32_e32 v5, 0x100, v0
	v_ashrrev_i32_e32 v10, 3, v5
	v_bfe_u32 v3, v0, 5, 1
	v_ashrrev_i32_e32 v11, 31, v10
	v_and_b32_e32 v14, 64, v188
	s_waitcnt lgkmcnt(0)
	s_add_u32 s48, s44, 0x22600000
	v_cmp_eq_u32_e32 vcc, 0, v3
	v_lshlrev_b64 v[12:13], 8, v[10:11]
	v_xor_b32_e32 v11, 32, v188
	v_add_u32_e32 v14, 64, v14
	v_ashrrev_i32_e32 v2, 1, v0
	s_addc_u32 s49, s45, 0
	s_movk_i32 s3, 0xffe0
	v_cndmask_b32_e64 v107, 0, 1.0, vcc
	v_and_b32_e32 v5, 7, v0
	v_cmp_lt_i32_e32 vcc, v11, v14
	v_readlane_b32 s38, v254, 60
	v_and_b32_e32 v1, 31, v0
	s_add_u32 s50, s44, 0x31600000
	v_bfi_b32 v106, s3, v2, v0
	v_lshlrev_b32_e32 v2, 3, v3
	v_lshlrev_b32_e32 v9, 4, v5
	s_waitcnt vmcnt(0)
	v_lshlrev_b32_e32 v108, 4, v3
	v_cndmask_b32_e32 v11, v188, v11, vcc
	s_movk_i32 s3, 0x470
	v_readlane_b32 s39, v254, 61
	s_addc_u32 s51, s45, 0
	v_lshlrev_b32_e32 v0, 2, v3
	v_sub_u32_e32 v3, v108, v2
	v_lshlrev_b32_e32 v109, 2, v11
	v_mul_lo_u32 v11, v4, s85
	v_lshlrev_b32_e32 v4, 1, v4
	v_mad_u32_u24 v5, v5, s3, v9
	v_mul_lo_u32 v14, v10, s85
	v_lshlrev_b32_e32 v10, 1, v10
	v_mul_u32_u24_e32 v110, 0x90, v1
	s_lshl_b32 s3, s38, 4
	s_lshl_b32 s52, s38, 17
	v_readlane_b32 s38, v253, 0
	s_mov_b32 s53, s81
	v_or_b32_e32 v111, 0x80, v0
	v_lshlrev_b32_e32 v96, 1, v2
	v_lshlrev_b32_e32 v128, 1, v8
	v_add_u32_e32 v112, v9, v11
	v_add_u32_e32 v113, v5, v4
	v_add_u32_e32 v114, v9, v14
	v_add_u32_e32 v115, v5, v10
	v_add_u32_e32 v116, v3, v110
	v_lshrrev_b32_e32 v168, 6, v133
	v_mul_u32_u24_e32 v166, 0x480, v168
	v_bfe_u32 v168, v133, 3, 3
	v_lshl_add_u32 v166, v168, 6, v166
	v_bfe_u32 v168, v133, 2, 1
	v_mul_u32_u24_e32 v168, 0x240, v168
	v_add_u32_e32 v166, v166, v168
	v_and_b32_e32 v168, 3, v133
	v_lshl_add_u32 v166, v168, 4, v166
	v_bfe_u32 v168, v133, 5, 1
	v_lshlrev_b32_e32 v167, 8, v168
	v_bfe_u32 v168, v133, 2, 2
	v_lshl_add_u32 v167, v168, 6, v167
	v_bfe_u32 v168, v133, 4, 1
	v_lshl_add_u32 v167, v168, 5, v167
	v_and_b32_e32 v168, 3, v133
	v_lshl_add_u32 v167, v168, 3, v167
	v_lshlrev_b32_e32 v98, 1, v0
	v_lshlrev_b64 v[100:101], 1, v[6:7]
	v_lshlrev_b64 v[102:103], 1, v[12:13]
	s_mov_b32 s31, s38
	v_readlane_b32 s39, v253, 1
	s_branch .LBB0_341

.LBB0_368:
	s_xor_b32 s101, s101, 0x4800
	s_add_i32 s94, s96, 1
	v_add_u32_e32 v168, s101, v112
	v_add_u32_e32 v170, s101, v166
	v_add_u32_e32 v169, s101, v114
	s_waitcnt vmcnt(3)
	ds_write_b128 v168, v[64:67]
	s_waitcnt vmcnt(2)
	ds_write_b128 v170, v[68:71] offset:9216
	s_waitcnt vmcnt(1)
	ds_write_b128 v169, v[80:83]
	s_waitcnt vmcnt(0)
	ds_write_b128 v170, v[88:91] offset:13824
	s_cmp_ge_u32 s94, s78
	s_waitcnt lgkmcnt(0)
	s_barrier
.LBB0_379:
	v_add3_u32 v122, v108, v110, s101
	v_add_u32_e32 v171, s101, v167
	ds_read_b128 v[192:195], v122
	ds_read_b128 v[196:199], v122 offset:4608
	ds_read_b128 v[200:203], v122 offset:32
	ds_read_b128 v[204:207], v122 offset:4640
	ds_read_b128 v[208:211], v122 offset:64
	ds_read_b128 v[212:215], v122 offset:4672
	ds_read_b128 v[216:219], v122 offset:96
	ds_read_b128 v[220:223], v122 offset:4704
	v_add_u32_e32 v127, s95, v97
	s_waitcnt lgkmcnt(7)
	v_mfma_f32_32x32x16_bf16 v[48:63], v[192:195], v[72:75], 0
	ds_read_b64_tr_b16 v[134:135], v171 offset:9216
	ds_read_b64_tr_b16 v[136:137], v171 offset:10368
	s_waitcnt lgkmcnt(8)
	v_mfma_f32_32x32x16_bf16 v[32:47], v[196:199], v[72:75], 0
	ds_read_b64_tr_b16 v[138:139], v171 offset:9792
	ds_read_b64_tr_b16 v[140:141], v171 offset:10944
	s_waitcnt lgkmcnt(9)
	v_mfma_f32_32x32x16_bf16 v[48:63], v[200:203], v[76:79], v[48:63]
	ds_read_b64_tr_b16 v[142:143], v171 offset:11520
	ds_read_b64_tr_b16 v[144:145], v171 offset:12672
	s_waitcnt lgkmcnt(10)
	v_mfma_f32_32x32x16_bf16 v[32:47], v[204:207], v[76:79], v[32:47]
	ds_read_b64_tr_b16 v[146:147], v171 offset:12096
	ds_read_b64_tr_b16 v[148:149], v171 offset:13248
	s_waitcnt lgkmcnt(11)
	v_mfma_f32_32x32x16_bf16 v[48:63], v[208:211], v[84:87], v[48:63]
	ds_read_b64_tr_b16 v[150:151], v171 offset:13824
	ds_read_b64_tr_b16 v[152:153], v171 offset:14976
	s_waitcnt lgkmcnt(12)
	v_mfma_f32_32x32x16_bf16 v[32:47], v[212:215], v[84:87], v[32:47]
	ds_read_b64_tr_b16 v[154:155], v171 offset:14400
	ds_read_b64_tr_b16 v[156:157], v171 offset:15552
	s_waitcnt lgkmcnt(13)
	v_mfma_f32_32x32x16_bf16 v[48:63], v[216:219], v[92:95], v[48:63]
	ds_read_b64_tr_b16 v[158:159], v171 offset:16128
	ds_read_b64_tr_b16 v[160:161], v171 offset:17280
	s_waitcnt lgkmcnt(14)
	v_mfma_f32_32x32x16_bf16 v[32:47], v[220:223], v[92:95], v[32:47]
	ds_read_b64_tr_b16 v[162:163], v171 offset:16704
	ds_read_b64_tr_b16 v[164:165], v171 offset:17856
	s_cbranch_scc1 .Lattn_pf_done
	s_and_b64 vcc, exec, s[56:57]
	s_cbranch_vccz .LBB0_371
	s_lshl_b64 s[66:67], s[80:81], 8
	s_add_u32 s66, s66, s58
	s_addc_u32 s67, s67, s59
	s_mov_b64 s[72:73], -1
	s_cbranch_execz .LBB0_372
	s_branch .LBB0_376
